# both diff-attn engines: K/V stage loads use SGPR base + 32-bit lane offsets (no 64-bit VALU address math)
# speedup vs baseline: 1.0067x; 1.0067x over previous
.LBB0_606:
	v_fma_f32 v20, v96, s72, -v116
	v_fma_f32 v21, v97, s72, -v116
	v_fma_f32 v25, v92, s72, -v116
	v_exp_f32_e32 v20, v20
	v_exp_f32_e32 v21, v21
	v_fma_f32 v22, v98, s72, -v116
	v_fma_f32 v23, v99, s72, -v116
	v_exp_f32_e32 v28, v25
	v_fma_f32 v25, v93, s72, -v116
	v_exp_f32_e32 v22, v22
	v_exp_f32_e32 v23, v23
	v_exp_f32_e32 v29, v25
	v_fma_f32 v25, v94, s72, -v116
	v_exp_f32_e32 v30, v25
	v_fma_f32 v25, v95, s72, -v116
	v_exp_f32_e32 v31, v25
	v_pk_add_f32 v[26:27], v[20:21], 0 op_sel_hi:[1,0]
	v_cvt_pk_bf16_f32 v20, v20, v21
	v_pk_add_f32 v[26:27], v[22:23], v[26:27]
	v_cvt_pk_bf16_f32 v21, v22, v23
	v_pk_add_f32 v[26:27], v[28:29], v[26:27]
	v_cvt_pk_bf16_f32 v22, v28, v29
	v_pk_add_f32 v[26:27], v[30:31], v[26:27]
	v_cvt_pk_bf16_f32 v23, v30, v31
	v_add_f32_e32 v25, v26, v27
	v_add_f32_e32 v25, v2, v25
	v_fma_f32 v2, v88, s72, -v3
	v_exp_f32_e32 v26, v2
	v_fma_f32 v2, v89, s72, -v3
	v_exp_f32_e32 v27, v2
	v_fma_f32 v2, v90, s72, -v3
	v_exp_f32_e32 v28, v2
	v_fma_f32 v2, v91, s72, -v3
	v_exp_f32_e32 v29, v2
	v_fma_f32 v2, v84, s72, -v3
	v_exp_f32_e32 v36, v2
	v_fma_f32 v2, v85, s72, -v3
	v_exp_f32_e32 v37, v2
	v_pk_add_f32 v[30:31], v[26:27], 0 op_sel_hi:[1,0]
	v_add_u32_e32 v0, v0, v157
	v_pk_add_f32 v[30:31], v[28:29], v[30:31]
	v_cvt_pk_bf16_f32 v26, v26, v27
	v_pk_add_f32 v[30:31], v[36:37], v[30:31]
	v_cvt_pk_bf16_f32 v27, v28, v29
	v_cvt_pk_bf16_f32 v28, v36, v37
	ds_read_b128 v[36:39], v0 offset:8192
	v_fma_f32 v2, v86, s72, -v3
	v_fma_f32 v3, v87, s72, -v3
	v_exp_f32_e32 v2, v2
	v_exp_f32_e32 v3, v3
	s_waitcnt lgkmcnt(0)
	v_mfma_f32_16x16x32_bf16 v[80:83], v[36:39], v[20:23], v[80:83]
	v_cvt_pk_bf16_f32 v29, v2, v3
	v_pk_add_f32 v[30:31], v[2:3], v[30:31]
	v_lshl_add_u32 v199, v200, 4, 0
	v_mfma_f32_16x16x32_bf16 v[76:79], v[36:39], v[26:29], v[76:79]
	ds_read_b128 v[36:39], v0 offset:10240
	v_add_f32_e32 v30, v30, v31
	v_add_f32_e32 v24, v24, v30
	s_waitcnt lgkmcnt(0)
	v_mfma_f32_16x16x32_bf16 v[72:75], v[36:39], v[20:23], v[72:75]
	v_add_u32_e32 v198, 0xc000, v199
	v_mov_b32_e32 v179, v178
	s_mov_b32 s19, 0
	v_mfma_f32_16x16x32_bf16 v[68:71], v[36:39], v[26:29], v[68:71]
	ds_read_b128 v[36:39], v0 offset:12288
	v_mov_b32_e32 v204, 0
	s_mov_b32 s0, 0
	s_waitcnt lgkmcnt(0)
	v_mfma_f32_16x16x32_bf16 v[64:67], v[36:39], v[20:23], v[64:67]
	v_mov_b64_e32 v[196:197], v[178:179]
	v_mfma_f32_16x16x32_bf16 v[60:63], v[36:39], v[26:29], v[60:63]
	ds_read_b128 v[36:39], v0 offset:14336
	s_waitcnt lgkmcnt(0)
	v_mfma_f32_16x16x32_bf16 v[56:59], v[36:39], v[20:23], v[56:59]
	v_mfma_f32_16x16x32_bf16 v[52:55], v[36:39], v[26:29], v[52:55]
	ds_read_b128 v[36:39], v0 offset:16384
	s_waitcnt lgkmcnt(0)
	v_mfma_f32_16x16x32_bf16 v[48:51], v[36:39], v[20:23], v[48:51]
	v_mfma_f32_16x16x32_bf16 v[44:47], v[36:39], v[26:29], v[44:47]
	ds_read_b128 v[36:39], v0 offset:18432
	s_waitcnt lgkmcnt(0)
	v_mfma_f32_16x16x32_bf16 v[40:43], v[36:39], v[20:23], v[40:43]
	v_mfma_f32_16x16x32_bf16 v[84:87], v[36:39], v[26:29], v[32:35]
	s_nop 2
	ds_read_b128 v[30:33], v0 offset:20480
	ds_read_b128 v[34:37], v0 offset:22528
	ds_swizzle_b32 v0, v25 offset:swizzle(SWAP,16)
	s_waitcnt lgkmcnt(0)
	s_barrier
	v_add_f32_e32 v0, v25, v0
	ds_bpermute_b32 v2, v156, v0
	s_waitcnt lgkmcnt(0)
	v_add_f32_e32 v0, v0, v2
	ds_swizzle_b32 v2, v24 offset:swizzle(SWAP,16)
	s_waitcnt lgkmcnt(0)
	v_add_f32_e32 v2, v24, v2
	ds_bpermute_b32 v3, v156, v2
	s_waitcnt lgkmcnt(0)
	v_add_f32_e32 v2, v2, v3
	v_div_scale_f32 v3, s[26:27], v0, v0, 1.0
	v_rcp_f32_e32 v24, v3
	s_nop 0
	v_fma_f32 v25, -v3, v24, 1.0
	v_fmac_f32_e32 v24, v25, v24
	v_div_scale_f32 v25, vcc, 1.0, v0, 1.0
	v_mul_f32_e32 v38, v25, v24
	v_fma_f32 v39, -v3, v38, v25
	v_fmac_f32_e32 v38, v39, v24
	v_fma_f32 v3, -v3, v38, v25
	v_div_fmas_f32 v3, v3, v24, v38
	v_div_fixup_f32 v182, v3, v0, 1.0
	v_div_scale_f32 v0, s[26:27], v2, v2, 1.0
	v_rcp_f32_e32 v3, v0
	v_mov_b32_e32 v183, v182
	v_fma_f32 v24, -v0, v3, 1.0
	v_fmac_f32_e32 v3, v24, v3
	v_div_scale_f32 v24, vcc, 1.0, v2, 1.0
	v_mul_f32_e32 v25, v24, v3
	v_fma_f32 v38, -v0, v25, v24
	v_fmac_f32_e32 v25, v38, v3
	v_fma_f32 v0, -v0, v25, v24
	v_div_fmas_f32 v0, v0, v3, v25
	v_div_fixup_f32 v180, v0, v2, 1.0
	v_mov_b32_e32 v181, v180
	v_pk_mul_f32 v[2:3], v[76:77], v[180:181] op_sel_hi:[1,0]
	s_nop 0
	v_cvt_pk_bf16_f32 v76, v2, v3
	v_pk_mul_f32 v[2:3], v[78:79], v[180:181] op_sel_hi:[1,0]
	s_nop 0
	v_cvt_pk_bf16_f32 v77, v2, v3
	v_pk_mul_f32 v[2:3], v[68:69], v[180:181] op_sel_hi:[1,0]
	s_nop 0
	v_cvt_pk_bf16_f32 v78, v2, v3
	v_pk_mul_f32 v[2:3], v[70:71], v[180:181] op_sel_hi:[1,0]
	s_nop 0
	v_cvt_pk_bf16_f32 v79, v2, v3
	v_pk_mul_f32 v[2:3], v[80:81], v[182:183] op_sel_hi:[1,0]
	s_nop 0
	v_cvt_pk_bf16_f32 v68, v2, v3
	v_pk_mul_f32 v[2:3], v[82:83], v[182:183] op_sel_hi:[1,0]
	s_nop 0
	v_cvt_pk_bf16_f32 v69, v2, v3
	v_pk_mul_f32 v[2:3], v[72:73], v[182:183] op_sel_hi:[1,0]
	s_nop 0
	v_cvt_pk_bf16_f32 v70, v2, v3
	v_pk_mul_f32 v[2:3], v[74:75], v[182:183] op_sel_hi:[1,0]
	s_nop 0
	v_cvt_pk_bf16_f32 v71, v2, v3
	v_pk_mul_f32 v[2:3], v[60:61], v[180:181] op_sel_hi:[1,0]
	ds_write_b128 v199, v[68:71] offset:49152
	ds_write_b128 v199, v[76:79] offset:61440
	v_cvt_pk_bf16_f32 v60, v2, v3
	v_pk_mul_f32 v[2:3], v[62:63], v[180:181] op_sel_hi:[1,0]
	v_mov_b32_e32 v78, v175
	v_cvt_pk_bf16_f32 v61, v2, v3
	v_pk_mul_f32 v[2:3], v[52:53], v[180:181] op_sel_hi:[1,0]
	s_nop 0
	v_cvt_pk_bf16_f32 v62, v2, v3
	v_pk_mul_f32 v[2:3], v[54:55], v[180:181] op_sel_hi:[1,0]
	s_nop 0
	v_cvt_pk_bf16_f32 v63, v2, v3
	v_pk_mul_f32 v[2:3], v[64:65], v[182:183] op_sel_hi:[1,0]
	s_nop 0
	v_cvt_pk_bf16_f32 v52, v2, v3
	v_pk_mul_f32 v[2:3], v[66:67], v[182:183] op_sel_hi:[1,0]
	s_nop 0
	v_cvt_pk_bf16_f32 v53, v2, v3
	v_pk_mul_f32 v[2:3], v[56:57], v[182:183] op_sel_hi:[1,0]
	s_nop 0
	v_cvt_pk_bf16_f32 v54, v2, v3
	v_pk_mul_f32 v[2:3], v[58:59], v[182:183] op_sel_hi:[1,0]
	s_nop 0
	v_cvt_pk_bf16_f32 v55, v2, v3
	v_pk_mul_f32 v[2:3], v[44:45], v[180:181] op_sel_hi:[1,0]
	ds_write_b128 v199, v[52:55] offset:53248
	ds_write_b128 v198, v[60:63] offset:16384
	v_cvt_pk_bf16_f32 v44, v2, v3
	v_pk_mul_f32 v[2:3], v[46:47], v[180:181] op_sel_hi:[1,0]
	s_nop 0
	v_cvt_pk_bf16_f32 v45, v2, v3
	v_pk_mul_f32 v[2:3], v[84:85], v[180:181] op_sel_hi:[1,0]
	s_nop 0
	v_cvt_pk_bf16_f32 v46, v2, v3
	v_pk_mul_f32 v[2:3], v[86:87], v[180:181] op_sel_hi:[1,0]
	s_nop 0
	v_cvt_pk_bf16_f32 v47, v2, v3
	v_pk_mul_f32 v[2:3], v[48:49], v[182:183] op_sel_hi:[1,0]
	s_nop 0
	v_cvt_pk_bf16_f32 v38, v2, v3
	v_pk_mul_f32 v[2:3], v[50:51], v[182:183] op_sel_hi:[1,0]
	s_nop 0
	v_cvt_pk_bf16_f32 v39, v2, v3
	v_pk_mul_f32 v[2:3], v[40:41], v[182:183] op_sel_hi:[1,0]
	s_nop 0
	v_cvt_pk_bf16_f32 v40, v2, v3
	v_pk_mul_f32 v[2:3], v[42:43], v[182:183] op_sel_hi:[1,0]
	s_nop 0
	v_cvt_pk_bf16_f32 v41, v2, v3
	ds_write_b128 v199, v[38:41] offset:57344
	ds_write_b128 v198, v[44:47] offset:20480
	s_nop 0
	v_and_b32_e32 v80, 15, v78
	v_ashrrev_i32_e32 v0, 1, v78
	v_and_or_b32 v2, v0, s96, v80
	v_ashrrev_i32_e32 v3, 31, v2
	v_lshlrev_b64 v[38:39], 14, v[2:3]
	v_or_b32_e32 v2, 16, v2
	v_and_b32_e32 v0, 48, v78
	v_ashrrev_i32_e32 v3, 31, v2
	v_lshl_add_u64 v[24:25], s[24:25], 0, v[0:1]
	v_lshlrev_b64 v[2:3], 14, v[2:3]
	v_ashrrev_i32_e32 v207, 3, v78
	v_lshl_add_u64 v[38:39], v[24:25], 0, v[38:39]
	v_lshl_add_u64 v[2:3], v[24:25], 0, v[2:3]
	v_lshrrev_b32_e32 v0, 1, v207
	global_load_dwordx4 v[46:49], v[38:39], off offset:128
	s_nop 0
	global_load_dwordx4 v[38:41], v[38:39], off offset:192
	s_nop 0
	global_load_dwordx4 v[50:53], v[2:3], off offset:128
	global_load_dwordx4 v[42:45], v[2:3], off offset:192
	v_xor_b32_e32 v0, v0, v78
	v_add_u32_e32 v2, s1, v207
	v_lshlrev_b32_e32 v0, 4, v0
	v_ashrrev_i32_e32 v3, 31, v2
	v_and_b32_e32 v208, 0x70, v0
	v_lshlrev_b64 v[2:3], 14, v[2:3]
	v_lshlrev_b32_e32 v0, 4, v78
	v_lshl_add_u64 v[2:3], s[14:15], 0, v[2:3]
	v_and_b32_e32 v0, 0x70, v0
	v_lshl_add_u64 v[2:3], v[2:3], 0, v[0:1]
	global_load_dwordx4 v[54:57], v[2:3], off offset:128
	v_add_co_u32_e32 v2, vcc, s61, v2
	v_lshl_add_u64 v[24:25], s[22:23], 0, v[0:1]
	s_nop 0
	v_addc_co_u32_e32 v3, vcc, 0, v3, vcc
	global_load_dwordx4 v[58:61], v[2:3], off offset:128
	v_mad_i64_i32 v[2:3], s[22:23], v207, s74, v[24:25]
	global_load_dwordx4 v[62:65], v[2:3], off
	v_add_u32_e32 v2, 32, v207
	v_mad_i64_i32 v[186:187], s[22:23], v2, s74, 0
	v_mad_i64_i32 v[2:3], s[22:23], v2, s74, v[24:25]
	global_load_dwordx4 v[66:69], v[2:3], off
	v_add_u32_e32 v2, 64, v207
	v_mad_i64_i32 v[188:189], s[22:23], v2, s74, 0
	v_mad_i64_i32 v[2:3], s[22:23], v2, s74, v[24:25]
	global_load_dwordx4 v[70:73], v[2:3], off
	v_add_u32_e32 v2, 0x60, v207
	v_mad_i64_i32 v[190:191], s[22:23], v2, s74, 0
	v_mad_i64_i32 v[2:3], s[22:23], v2, s74, v[24:25]
	global_load_dwordx4 v[74:77], v[2:3], off
	v_lshlrev_b32_e32 v209, 7, v207
	v_or_b32_e32 v210, v208, v209
	v_and_b32_e32 v79, 63, v78
	v_bfe_u32 v81, v78, 4, 2
	v_add_u32_e32 v2, 0, v210
	v_lshl_add_u64 v[192:193], s[14:15], 0, v[0:1]
	v_lshrrev_b32_e32 v0, 1, v78
	s_waitcnt vmcnt(5)
	ds_write_b128 v2, v[54:57]
	s_waitcnt vmcnt(4)
	ds_write_b128 v2, v[58:61] offset:4096
	s_waitcnt vmcnt(3)
	ds_write_b128 v2, v[62:65] offset:8192
	s_waitcnt vmcnt(2)
	ds_write_b128 v2, v[66:69] offset:12288
	s_waitcnt vmcnt(1)
	ds_write_b128 v2, v[70:73] offset:16384
	s_waitcnt vmcnt(0)
	ds_write_b128 v2, v[74:77] offset:20480
	v_bfe_u32 v2, v78, 1, 3
	v_lshlrev_b32_e32 v3, 2, v79
	v_bitop3_b32 v0, v81, v0, 7 bitop3:0x78
	v_xor_b32_e32 v202, 0x80, v3
	v_lshlrev_b32_e32 v205, 4, v0
	v_bitop3_b32 v0, v81, v2, 4 bitop3:0x36
	v_mov_b32_e32 v2, v1
	v_mov_b32_e32 v3, v1
	v_lshlrev_b32_e32 v206, 7, v80
	v_lshlrev_b32_e32 v203, 4, v0
	v_mov_b32_e32 v0, v1
	v_mov_b64_e32 v[56:57], v[2:3]
	v_mov_b64_e32 v[64:65], v[2:3]
	v_mov_b64_e32 v[60:61], v[2:3]
	v_mov_b64_e32 v[72:73], v[2:3]
	v_mov_b64_e32 v[68:69], v[2:3]
	v_mov_b64_e32 v[76:77], v[2:3]
	v_mov_b64_e32 v[80:81], v[2:3]
	v_mov_b64_e32 v[84:85], v[2:3]
	v_mov_b64_e32 v[88:89], v[2:3]
	v_mov_b64_e32 v[92:93], v[2:3]
	v_mov_b64_e32 v[96:97], v[2:3]
	v_mov_b64_e32 v[100:101], v[2:3]
	v_mov_b64_e32 v[104:105], v[2:3]
	v_mov_b64_e32 v[108:109], v[2:3]
	v_mov_b64_e32 v[112:113], v[2:3]
	v_mov_b64_e32 v[116:117], v[2:3]
	v_mad_i64_i32 v[184:185], s[22:23], v207, s74, 0
	v_mov_b64_e32 v[54:55], v[0:1]
	v_mov_b64_e32 v[62:63], v[0:1]
	v_mov_b64_e32 v[58:59], v[0:1]
	v_mov_b64_e32 v[70:71], v[0:1]
	v_mov_b64_e32 v[66:67], v[0:1]
	v_mov_b64_e32 v[74:75], v[0:1]
	v_mov_b64_e32 v[78:79], v[0:1]
	v_mov_b64_e32 v[82:83], v[0:1]
	v_mov_b64_e32 v[86:87], v[0:1]
	v_mov_b64_e32 v[90:91], v[0:1]
	v_mov_b64_e32 v[94:95], v[0:1]
	v_mov_b64_e32 v[98:99], v[0:1]
	v_mov_b64_e32 v[102:103], v[0:1]
	v_mov_b64_e32 v[106:107], v[0:1]
	v_mov_b64_e32 v[110:111], v[0:1]
	v_mov_b64_e32 v[114:115], v[0:1]
	v_mov_b32_e32 v0, 0
	v_readfirstlane_b32 s100, v24
	v_readfirstlane_b32 s101, v25
	v_subrev_u32_e32 v25, s14, v192
	v_lshl_add_u32 v192, v207, 14, v25
	v_add_u32_e32 v193, 0x80000, v192
	v_add_u32_e32 v184, v184, v25
	v_add_u32_e32 v186, v186, v25
	v_add_u32_e32 v188, v188, v25
	v_add_u32_e32 v190, v190, v25

.LBB0_611:
	s_bitcmp1_b32 s0, 0
	s_cselect_b32 s0, 0x6000, 0
	s_add_i32 s24, s0, 0
	s_add_i32 s19, s19, 64
	s_add_i32 s0, s27, 0x1000
	s_and_b64 s[22:23], s[22:23], exec
	s_cselect_b32 s42, s19, s0
	s_lshl_b32 vcc_lo, s26, 14
	s_add_u32 vcc_lo, s14, vcc_lo
	s_addc_u32 vcc_hi, s15, 0
	global_load_dwordx4 v[118:121], v192, vcc offset:128
	global_load_dwordx4 v[122:125], v193, vcc offset:128
	s_lshl_b32 vcc_lo, s42, 1
	s_add_u32 vcc_lo, s100, vcc_lo
	s_addc_u32 vcc_hi, s101, 0
	global_load_dwordx4 v[126:129], v184, vcc
	global_load_dwordx4 v[138:141], v190, vcc
	v_add3_u32 v2, s24, v205, v206
	global_load_dwordx4 v[130:133], v186, vcc
	ds_read_b128 v[142:145], v2
	ds_read_b128 v[150:153], v2 offset:2048
	global_load_dwordx4 v[134:137], v188, vcc
	v_add3_u32 v3, s24, v203, v206
	ds_read_b128 v[158:161], v3
	ds_read_b128 v[234:237], v3 offset:4096
	s_waitcnt lgkmcnt(3)
	v_mfma_f32_16x16x32_bf16 v[146:149], v[142:145], v[46:49], 0
	v_mfma_f32_16x16x32_bf16 v[142:145], v[142:145], v[50:53], 0
	s_waitcnt lgkmcnt(1)
	v_mfma_f32_16x16x32_bf16 v[170:173], v[158:161], v[38:41], v[146:149]
	v_mfma_f32_16x16x32_bf16 v[158:161], v[158:161], v[42:45], v[142:145]
	s_nop 4
	ds_read_b128 v[142:145], v3 offset:2048
	v_mfma_f32_16x16x32_bf16 v[154:157], v[150:153], v[46:49], 0
	v_mfma_f32_16x16x32_bf16 v[150:153], v[150:153], v[50:53], 0
	s_waitcnt lgkmcnt(0)
	v_mfma_f32_16x16x32_bf16 v[166:169], v[142:145], v[38:41], v[154:157]
	v_mfma_f32_16x16x32_bf16 v[162:165], v[142:145], v[42:45], v[150:153]
	ds_read_b128 v[142:145], v2 offset:4096
	s_nop 3
	ds_read_b128 v[150:153], v2 offset:6144
	s_waitcnt lgkmcnt(1)
	v_mfma_f32_16x16x32_bf16 v[146:149], v[142:145], v[46:49], 0
	v_max3_f32 v2, v170, v171, v172
	s_nop 0
	v_max3_f32 v2, v2, v173, v166
	s_waitcnt lgkmcnt(0)
	v_mfma_f32_16x16x32_bf16 v[154:157], v[150:153], v[46:49], 0
	v_max3_f32 v2, v2, v167, v168
	s_nop 0
	v_max3_f32 v2, v2, v169, v169
	v_mfma_f32_16x16x32_bf16 v[226:229], v[150:153], v[50:53], 0
	v_mul_f32_e32 v2, 0x3e38aa3b, v2
	v_mfma_f32_16x16x32_bf16 v[150:153], v[234:237], v[38:41], v[146:149]
	s_nop 2
	ds_read_b128 v[146:149], v3 offset:6144
	v_mfma_f32_16x16x32_bf16 v[142:145], v[142:145], v[50:53], 0
	v_add_f32_e32 v3, 0x41000000, v196
	v_cmp_gt_f32_e32 vcc, v2, v3
	v_mfma_f32_16x16x32_bf16 v[142:145], v[234:237], v[42:45], v[142:145]
	s_waitcnt lgkmcnt(0)
	v_mfma_f32_16x16x32_bf16 v[154:157], v[146:149], v[38:41], v[154:157]
	v_mfma_f32_16x16x32_bf16 v[146:149], v[146:149], v[42:45], v[226:229]
	s_cbranch_vccz .LBB0_613
	ds_swizzle_b32 v3, v2 offset:swizzle(SWAP,16)
	v_max_f32_e32 v2, v2, v2
	v_mov_b32_e32 v195, v197
	s_waitcnt lgkmcnt(0)
	v_max_f32_e32 v3, v3, v3
	v_max_f32_e32 v2, v2, v3
	ds_bpermute_b32 v3, v202, v2
	s_waitcnt lgkmcnt(0)
	v_max3_f32 v194, v196, v2, v3
	v_sub_f32_e32 v2, v196, v194
	v_exp_f32_e32 v2, v2
	v_mov_b32_e32 v196, v194
	v_mul_f32_e32 v0, v0, v2
	v_pk_mul_f32 v[116:117], v[116:117], v[2:3] op_sel_hi:[1,0]
	v_pk_mul_f32 v[114:115], v[114:115], v[2:3] op_sel_hi:[1,0]
	v_pk_mul_f32 v[108:109], v[108:109], v[2:3] op_sel_hi:[1,0]
	v_pk_mul_f32 v[106:107], v[106:107], v[2:3] op_sel_hi:[1,0]
	v_pk_mul_f32 v[100:101], v[100:101], v[2:3] op_sel_hi:[1,0]
	v_pk_mul_f32 v[98:99], v[98:99], v[2:3] op_sel_hi:[1,0]
	v_pk_mul_f32 v[92:93], v[92:93], v[2:3] op_sel_hi:[1,0]
	v_pk_mul_f32 v[90:91], v[90:91], v[2:3] op_sel_hi:[1,0]
	v_pk_mul_f32 v[84:85], v[84:85], v[2:3] op_sel_hi:[1,0]
	v_pk_mul_f32 v[82:83], v[82:83], v[2:3] op_sel_hi:[1,0]
	v_pk_mul_f32 v[76:77], v[76:77], v[2:3] op_sel_hi:[1,0]
	v_pk_mul_f32 v[74:75], v[74:75], v[2:3] op_sel_hi:[1,0]
	v_pk_mul_f32 v[72:73], v[72:73], v[2:3] op_sel_hi:[1,0]
	v_pk_mul_f32 v[70:71], v[70:71], v[2:3] op_sel_hi:[1,0]
	v_pk_mul_f32 v[64:65], v[64:65], v[2:3] op_sel_hi:[1,0]
	v_pk_mul_f32 v[62:63], v[62:63], v[2:3] op_sel_hi:[1,0]
	s_branch .LBB0_614
